# lever4 on the attention mixer: one static s_setprio 1 for waves 4-7 for the whole phase so the two waves of a SIMD desynchronise (one in MFMA sections while the other is in softmax VALU)
# baseline (speedup 1.0000x reference)
.LBB0_41:
	s_bitcmp1_b32 s28, 8
	s_cbranch_scc0 .Latp_skip
	s_setprio 1

.LBB0_106:
	s_setprio 0
	s_mov_b32 s100, 0
	s_barrier
	s_mov_b64 s[2:3], 0
	s_mov_b32 s35, 0x2aaaaaab
	s_mov_b32 s38, 0x30000
